# v29 + priority 2 for GEMM epilogues and the following tile header (from the end of the last K-step's MFMAs until the next K-loop raises it to 3)
# speedup vs baseline: 1.0004x; 1.0004x over previous
.LBB0_303:
	s_setprio 3
	s_and_b32 s1, s0, 0x2000
	s_xor_b32 s8, s1, 0x2000
	s_lshl_b32 s101, s8, 1
	s_add_u32 s101, s101, s100
	s_add_u32 m0, s101, 0x0
	s_nop 0
	global_load_lds_dwordx4 v[184:185], off
	s_add_u32 m0, s101, 0x1000
	v_lshl_add_u64 v[184:185], v[184:185], 0, vcc
	global_load_lds_dwordx4 v[186:187], off
	s_add_u32 m0, s101, 0x2000
	v_lshl_add_u64 v[186:187], v[186:187], 0, vcc
	global_load_lds_dwordx4 v[188:189], off
	s_add_u32 m0, s101, 0x3000
	v_lshl_add_u64 v[188:189], v[188:189], 0, vcc
	global_load_lds_dwordx4 v[190:191], off
	s_add_u32 m0, s101, 0x8000
	v_lshl_add_u64 v[190:191], v[190:191], 0, vcc
	global_load_lds_dwordx4 v[192:193], off
	s_add_u32 m0, s101, 0x9000
	v_lshl_add_u64 v[192:193], v[192:193], 0, vcc
	global_load_lds_dwordx4 v[194:195], off
	s_add_u32 m0, s101, 0xa000
	v_lshl_add_u64 v[194:195], v[194:195], 0, vcc
	global_load_lds_dwordx4 v[196:197], off
	s_add_u32 m0, s101, 0xb000
	v_lshl_add_u64 v[196:197], v[196:197], 0, vcc
	global_load_lds_dwordx4 v[198:199], off
	v_lshl_add_u64 v[198:199], v[198:199], 0, vcc
	s_lshl_b32 s1, s1, 1
	v_add_u32_e32 v82, s1, v86
	v_add_u32_e32 v83, s1, v85
	v_add_u32_e32 v95, v82, v93
	ds_read_b128 v[96:99], v95
	ds_read_b128 v[100:103], v95 offset:2048
	ds_read_b128 v[120:123], v95 offset:4096
	ds_read_b128 v[124:127], v95 offset:6144
	v_add_u32_e32 v95, v83, v93
	ds_read_b128 v[128:131], v95 offset:32768
	ds_read_b128 v[132:135], v95 offset:34816
	ds_read_b128 v[136:139], v95 offset:36864
	ds_read_b128 v[140:143], v95 offset:38912
	s_setprio 1
	s_waitcnt lgkmcnt(0)
	v_mfma_f32_16x16x32_bf16 v[60:63], v[128:131], v[96:99], v[60:63]
	v_mfma_f32_16x16x32_bf16 v[56:59], v[132:135], v[96:99], v[56:59]
	v_mfma_f32_16x16x32_bf16 v[52:55], v[136:139], v[96:99], v[52:55]
	v_mfma_f32_16x16x32_bf16 v[48:51], v[140:143], v[96:99], v[48:51]
	v_mfma_f32_16x16x32_bf16 v[44:47], v[128:131], v[100:103], v[44:47]
	v_mfma_f32_16x16x32_bf16 v[40:43], v[132:135], v[100:103], v[40:43]
	v_mfma_f32_16x16x32_bf16 v[36:39], v[136:139], v[100:103], v[36:39]
	v_mfma_f32_16x16x32_bf16 v[32:35], v[140:143], v[100:103], v[32:35]
	v_mfma_f32_16x16x32_bf16 v[28:31], v[128:131], v[120:123], v[28:31]
	v_mfma_f32_16x16x32_bf16 v[24:27], v[132:135], v[120:123], v[24:27]
	v_mfma_f32_16x16x32_bf16 v[20:23], v[136:139], v[120:123], v[20:23]
	v_mfma_f32_16x16x32_bf16 v[16:19], v[140:143], v[120:123], v[16:19]
	v_mfma_f32_16x16x32_bf16 v[12:15], v[128:131], v[124:127], v[12:15]
	v_mfma_f32_16x16x32_bf16 v[8:11], v[132:135], v[124:127], v[8:11]
	v_mfma_f32_16x16x32_bf16 v[4:7], v[136:139], v[124:127], v[4:7]
	v_mfma_f32_16x16x32_bf16 v[0:3], v[140:143], v[124:127], v[0:3]
	s_setprio 0
	v_add_u32_e32 v82, v82, v94
	ds_read_b128 v[96:99], v82
	ds_read_b128 v[100:103], v82 offset:2048
	ds_read_b128 v[120:123], v82 offset:4096
	ds_read_b128 v[124:127], v82 offset:6144
	v_add_u32_e32 v82, v83, v94
	ds_read_b128 v[128:131], v82 offset:32768
	ds_read_b128 v[132:135], v82 offset:34816
	ds_read_b128 v[136:139], v82 offset:36864
	ds_read_b128 v[140:143], v82 offset:38912
	s_setprio 1
	s_waitcnt lgkmcnt(0)
	v_mfma_f32_16x16x32_bf16 v[60:63], v[128:131], v[96:99], v[60:63]
	v_mfma_f32_16x16x32_bf16 v[56:59], v[132:135], v[96:99], v[56:59]
	v_mfma_f32_16x16x32_bf16 v[52:55], v[136:139], v[96:99], v[52:55]
	v_mfma_f32_16x16x32_bf16 v[48:51], v[140:143], v[96:99], v[48:51]
	v_mfma_f32_16x16x32_bf16 v[44:47], v[128:131], v[100:103], v[44:47]
	v_mfma_f32_16x16x32_bf16 v[40:43], v[132:135], v[100:103], v[40:43]
	v_mfma_f32_16x16x32_bf16 v[36:39], v[136:139], v[100:103], v[36:39]
	v_mfma_f32_16x16x32_bf16 v[32:35], v[140:143], v[100:103], v[32:35]
	v_mfma_f32_16x16x32_bf16 v[28:31], v[128:131], v[120:123], v[28:31]
	v_mfma_f32_16x16x32_bf16 v[24:27], v[132:135], v[120:123], v[24:27]
	v_mfma_f32_16x16x32_bf16 v[20:23], v[136:139], v[120:123], v[20:23]
	v_mfma_f32_16x16x32_bf16 v[16:19], v[140:143], v[120:123], v[16:19]
	v_mfma_f32_16x16x32_bf16 v[12:15], v[128:131], v[124:127], v[12:15]
	v_mfma_f32_16x16x32_bf16 v[8:11], v[132:135], v[124:127], v[8:11]
	v_mfma_f32_16x16x32_bf16 v[4:7], v[136:139], v[124:127], v[4:7]
	v_mfma_f32_16x16x32_bf16 v[0:3], v[140:143], v[124:127], v[0:3]
	s_setprio 0
	s_addk_i32 s0, 0x2000
	s_waitcnt vmcnt(0)
	s_add_u32 s20, s20, 0x80
	s_addc_u32 s21, s21, 0
	s_cmpk_lg_i32 s20, 0x780
	s_waitcnt vmcnt(0)
	s_barrier
	s_cbranch_scc1 .LBB0_303
	ds_read_b128 v[78:81], v89 offset:55296
	ds_read_b128 v[96:99], v89 offset:53248
	ds_read_b128 v[100:103], v89 offset:51200
	ds_read_b128 v[120:123], v89 offset:49152
	ds_read_b128 v[124:127], v90 offset:22528
	ds_read_b128 v[128:131], v90 offset:20480
	ds_read_b128 v[132:135], v90 offset:18432
	ds_read_b128 v[136:139], v90 offset:16384
	s_setprio 1
	s_waitcnt lgkmcnt(0)
	v_mfma_f32_16x16x32_bf16 v[60:63], v[120:123], v[136:139], v[60:63]
	v_mfma_f32_16x16x32_bf16 v[56:59], v[100:103], v[136:139], v[56:59]
	v_mfma_f32_16x16x32_bf16 v[52:55], v[96:99], v[136:139], v[52:55]
	v_mfma_f32_16x16x32_bf16 v[48:51], v[78:81], v[136:139], v[48:51]
	v_mfma_f32_16x16x32_bf16 v[44:47], v[120:123], v[132:135], v[44:47]
	v_mfma_f32_16x16x32_bf16 v[40:43], v[100:103], v[132:135], v[40:43]
	v_mfma_f32_16x16x32_bf16 v[36:39], v[96:99], v[132:135], v[36:39]
	v_mfma_f32_16x16x32_bf16 v[32:35], v[78:81], v[132:135], v[32:35]
	v_mfma_f32_16x16x32_bf16 v[28:31], v[120:123], v[128:131], v[28:31]
	v_mfma_f32_16x16x32_bf16 v[24:27], v[100:103], v[128:131], v[24:27]
	v_mfma_f32_16x16x32_bf16 v[20:23], v[96:99], v[128:131], v[20:23]
	v_mfma_f32_16x16x32_bf16 v[16:19], v[78:81], v[128:131], v[16:19]
	v_mfma_f32_16x16x32_bf16 v[12:15], v[120:123], v[124:127], v[12:15]
	v_mfma_f32_16x16x32_bf16 v[8:11], v[100:103], v[124:127], v[8:11]
	v_mfma_f32_16x16x32_bf16 v[4:7], v[96:99], v[124:127], v[4:7]
	v_mfma_f32_16x16x32_bf16 v[0:3], v[78:81], v[124:127], v[0:3]
	s_setprio 0
	ds_read_b128 v[78:81], v91 offset:16384
	ds_read_b128 v[96:99], v91 offset:18432
	ds_read_b128 v[100:103], v91 offset:20480
	ds_read_b128 v[120:123], v91 offset:22528
	ds_read_b128 v[124:127], v92 offset:49152
	ds_read_b128 v[128:131], v92 offset:51200
	ds_read_b128 v[132:135], v92 offset:53248
	ds_read_b128 v[136:139], v92 offset:55296
	s_setprio 1
	s_waitcnt lgkmcnt(3)
	v_mfma_f32_16x16x32_bf16 v[60:63], v[124:127], v[78:81], v[60:63]
	s_waitcnt lgkmcnt(2)
	v_mfma_f32_16x16x32_bf16 v[56:59], v[128:131], v[78:81], v[56:59]
	s_waitcnt lgkmcnt(1)
	v_mfma_f32_16x16x32_bf16 v[52:55], v[132:135], v[78:81], v[52:55]
	s_waitcnt lgkmcnt(0)
	v_mfma_f32_16x16x32_bf16 v[48:51], v[136:139], v[78:81], v[48:51]
	v_mfma_f32_16x16x32_bf16 v[44:47], v[124:127], v[96:99], v[44:47]
	v_mfma_f32_16x16x32_bf16 v[40:43], v[128:131], v[96:99], v[40:43]
	v_mfma_f32_16x16x32_bf16 v[36:39], v[132:135], v[96:99], v[36:39]
	v_mfma_f32_16x16x32_bf16 v[32:35], v[136:139], v[96:99], v[32:35]
	v_mfma_f32_16x16x32_bf16 v[28:31], v[124:127], v[100:103], v[28:31]
	v_mfma_f32_16x16x32_bf16 v[24:27], v[128:131], v[100:103], v[24:27]
	v_mfma_f32_16x16x32_bf16 v[20:23], v[132:135], v[100:103], v[20:23]
	v_mfma_f32_16x16x32_bf16 v[16:19], v[136:139], v[100:103], v[16:19]
	v_mfma_f32_16x16x32_bf16 v[12:15], v[124:127], v[120:123], v[12:15]
	v_mfma_f32_16x16x32_bf16 v[8:11], v[128:131], v[120:123], v[8:11]
	v_mfma_f32_16x16x32_bf16 v[4:7], v[132:135], v[120:123], v[4:7]
	v_mfma_f32_16x16x32_bf16 v[0:3], v[136:139], v[120:123], v[0:3]
	s_setprio 2
	s_waitcnt vmcnt(0)
	s_cmp_lt_i32 s10, 32
	s_mov_b64 s[0:1], -1
	s_barrier
	s_cbranch_scc1 .LBB0_594
	s_cmp_eq_u32 s10, 32
	s_cselect_b64 s[0:1], -1, 0
	s_and_b64 vcc, exec, s[0:1]
	v_mov_b32_e32 v79, v63
	v_mov_b32_e32 v82, v62
	v_mov_b32_e32 v83, v61
	v_mov_b32_e32 v95, v60
	s_cbranch_vccz .LBB0_323
	v_cmp_nlt_f32_e64 s[8:9], |v60|, s33
	s_and_saveexec_b64 s[12:13], s[8:9]
	s_xor_b64 s[8:9], exec, s[12:13]
	s_cbranch_execz .LBB0_308
	v_add_f32_e64 v78, |v60|, |v60|
	v_mul_f32_e32 v79, 0x3fb8aa3b, v78
	v_rndne_f32_e32 v80, v79
	s_mov_b32 s11, 0x3fb8aa3b
	v_sub_f32_e32 v81, v79, v80
	v_fma_f32 v79, v78, s11, -v79
	v_fmac_f32_e32 v79, 0x32a5705f, v78
	v_add_f32_e32 v79, v81, v79
	v_cvt_i32_f32_e32 v80, v80
	v_exp_f32_e32 v79, v79
	s_mov_b32 s11, 0xc2ce8ed0
	v_cmp_ngt_f32_e32 vcc, s11, v78
	s_mov_b32 s11, 0x42b17218
	v_ldexp_f32 v79, v79, v80
	v_cndmask_b32_e32 v79, 0, v79, vcc
	v_cmp_nlt_f32_e32 vcc, s11, v78
	s_nop 1
	v_cndmask_b32_e32 v78, v112, v79, vcc
	v_add_f32_e32 v78, 1.0, v78
	v_rcp_f32_e32 v78, v78
	s_nop 0
	v_fma_f32 v78, v78, -2.0, 1.0

.LBB0_882:
	s_setprio 3
	s_and_b32 s6, s0, 0x2000
	s_xor_b32 s8, s6, 0x2000
	s_lshl_b32 s101, s8, 1
	s_add_u32 s101, s101, s100
	s_add_u32 m0, s101, 0x0
	s_nop 0
	global_load_lds_dwordx4 v[184:185], off
	s_add_u32 m0, s101, 0x1000
	v_lshl_add_u64 v[184:185], v[184:185], 0, vcc
	global_load_lds_dwordx4 v[186:187], off
	s_add_u32 m0, s101, 0x2000
	v_lshl_add_u64 v[186:187], v[186:187], 0, vcc
	global_load_lds_dwordx4 v[188:189], off
	s_add_u32 m0, s101, 0x3000
	v_lshl_add_u64 v[188:189], v[188:189], 0, vcc
	global_load_lds_dwordx4 v[190:191], off
	s_add_u32 m0, s101, 0x8000
	v_lshl_add_u64 v[190:191], v[190:191], 0, vcc
	global_load_lds_dwordx4 v[192:193], off
	s_add_u32 m0, s101, 0x9000
	v_lshl_add_u64 v[192:193], v[192:193], 0, vcc
	global_load_lds_dwordx4 v[194:195], off
	s_add_u32 m0, s101, 0xa000
	v_lshl_add_u64 v[194:195], v[194:195], 0, vcc
	global_load_lds_dwordx4 v[196:197], off
	s_add_u32 m0, s101, 0xb000
	v_lshl_add_u64 v[196:197], v[196:197], 0, vcc
	global_load_lds_dwordx4 v[198:199], off
	v_lshl_add_u64 v[198:199], v[198:199], 0, vcc
	s_lshl_b32 s6, s6, 1
	v_add_u32_e32 v102, s6, v90
	v_add_u32_e32 v103, s6, v71
	v_add_u32_e32 v128, v102, v96
	v_add_u32_e32 v144, v103, v96
	ds_read_b128 v[98:101], v128
	ds_read_b128 v[120:123], v128 offset:2048
	ds_read_b128 v[124:127], v128 offset:4096
	ds_read_b128 v[128:131], v128 offset:6144
	ds_read_b128 v[132:135], v144 offset:32768
	ds_read_b128 v[136:139], v144 offset:34816
	ds_read_b128 v[140:143], v144 offset:36864
	ds_read_b128 v[144:147], v144 offset:38912
	s_setprio 1
	s_waitcnt lgkmcnt(0)
	v_mfma_f32_16x16x32_bf16 v[60:63], v[132:135], v[98:101], v[60:63]
	v_mfma_f32_16x16x32_bf16 v[56:59], v[136:139], v[98:101], v[56:59]
	v_mfma_f32_16x16x32_bf16 v[52:55], v[140:143], v[98:101], v[52:55]
	v_mfma_f32_16x16x32_bf16 v[48:51], v[144:147], v[98:101], v[48:51]
	v_mfma_f32_16x16x32_bf16 v[44:47], v[132:135], v[120:123], v[44:47]
	v_mfma_f32_16x16x32_bf16 v[40:43], v[136:139], v[120:123], v[40:43]
	v_mfma_f32_16x16x32_bf16 v[36:39], v[140:143], v[120:123], v[36:39]
	v_mfma_f32_16x16x32_bf16 v[32:35], v[144:147], v[120:123], v[32:35]
	v_mfma_f32_16x16x32_bf16 v[28:31], v[132:135], v[124:127], v[28:31]
	v_mfma_f32_16x16x32_bf16 v[24:27], v[136:139], v[124:127], v[24:27]
	v_mfma_f32_16x16x32_bf16 v[20:23], v[140:143], v[124:127], v[20:23]
	v_mfma_f32_16x16x32_bf16 v[16:19], v[144:147], v[124:127], v[16:19]
	v_mfma_f32_16x16x32_bf16 v[12:15], v[132:135], v[128:131], v[12:15]
	v_mfma_f32_16x16x32_bf16 v[8:11], v[136:139], v[128:131], v[8:11]
	v_mfma_f32_16x16x32_bf16 v[4:7], v[140:143], v[128:131], v[4:7]
	v_mfma_f32_16x16x32_bf16 v[0:3], v[144:147], v[128:131], v[0:3]
	s_setprio 0
	v_add_u32_e32 v102, v102, v97
	ds_read_b128 v[98:101], v102
	ds_read_b128 v[120:123], v102 offset:2048
	ds_read_b128 v[124:127], v102 offset:4096
	ds_read_b128 v[128:131], v102 offset:6144
	v_add_u32_e32 v102, v103, v97
	ds_read_b128 v[132:135], v102 offset:32768
	ds_read_b128 v[136:139], v102 offset:34816
	ds_read_b128 v[140:143], v102 offset:36864
	ds_read_b128 v[144:147], v102 offset:38912
	s_setprio 1
	s_waitcnt lgkmcnt(0)
	v_mfma_f32_16x16x32_bf16 v[60:63], v[132:135], v[98:101], v[60:63]
	v_mfma_f32_16x16x32_bf16 v[56:59], v[136:139], v[98:101], v[56:59]
	v_mfma_f32_16x16x32_bf16 v[52:55], v[140:143], v[98:101], v[52:55]
	v_mfma_f32_16x16x32_bf16 v[48:51], v[144:147], v[98:101], v[48:51]
	v_mfma_f32_16x16x32_bf16 v[44:47], v[132:135], v[120:123], v[44:47]
	v_mfma_f32_16x16x32_bf16 v[40:43], v[136:139], v[120:123], v[40:43]
	v_mfma_f32_16x16x32_bf16 v[36:39], v[140:143], v[120:123], v[36:39]
	v_mfma_f32_16x16x32_bf16 v[32:35], v[144:147], v[120:123], v[32:35]
	v_mfma_f32_16x16x32_bf16 v[28:31], v[132:135], v[124:127], v[28:31]
	v_mfma_f32_16x16x32_bf16 v[24:27], v[136:139], v[124:127], v[24:27]
	v_mfma_f32_16x16x32_bf16 v[20:23], v[140:143], v[124:127], v[20:23]
	v_mfma_f32_16x16x32_bf16 v[16:19], v[144:147], v[124:127], v[16:19]
	v_mfma_f32_16x16x32_bf16 v[12:15], v[132:135], v[128:131], v[12:15]
	v_mfma_f32_16x16x32_bf16 v[8:11], v[136:139], v[128:131], v[8:11]
	v_mfma_f32_16x16x32_bf16 v[4:7], v[140:143], v[128:131], v[4:7]
	v_mfma_f32_16x16x32_bf16 v[0:3], v[144:147], v[128:131], v[0:3]
	s_setprio 0
	s_waitcnt vmcnt(0)
	s_add_u32 s36, s36, 0x80
	s_addc_u32 s37, s37, 0
	s_addk_i32 s0, 0x2000
	s_cmpk_lg_i32 s36, 0x780
	s_waitcnt vmcnt(0)
	s_barrier
	s_cbranch_scc1 .LBB0_882
	ds_read_b128 v[86:89], v92 offset:16384
	ds_read_b128 v[98:101], v92 offset:18432
	ds_read_b128 v[120:123], v92 offset:20480
	ds_read_b128 v[124:127], v92 offset:22528
	ds_read_b128 v[128:131], v93 offset:49152
	ds_read_b128 v[132:135], v93 offset:51200
	ds_read_b128 v[136:139], v93 offset:53248
	ds_read_b128 v[140:143], v93 offset:55296
	s_setprio 1
	s_waitcnt lgkmcnt(3)
	v_mfma_f32_16x16x32_bf16 v[60:63], v[128:131], v[86:89], v[60:63]
	s_waitcnt lgkmcnt(2)
	v_mfma_f32_16x16x32_bf16 v[56:59], v[132:135], v[86:89], v[56:59]
	s_waitcnt lgkmcnt(1)
	v_mfma_f32_16x16x32_bf16 v[52:55], v[136:139], v[86:89], v[52:55]
	s_waitcnt lgkmcnt(0)
	v_mfma_f32_16x16x32_bf16 v[48:51], v[140:143], v[86:89], v[48:51]
	v_mfma_f32_16x16x32_bf16 v[40:43], v[132:135], v[98:101], v[40:43]
	v_mfma_f32_16x16x32_bf16 v[36:39], v[136:139], v[98:101], v[36:39]
	v_mfma_f32_16x16x32_bf16 v[32:35], v[140:143], v[98:101], v[32:35]
	v_mfma_f32_16x16x32_bf16 v[20:23], v[136:139], v[120:123], v[20:23]
	v_mfma_f32_16x16x32_bf16 v[16:19], v[140:143], v[120:123], v[16:19]
	v_mfma_f32_16x16x32_bf16 v[0:3], v[140:143], v[124:127], v[0:3]
	v_mfma_f32_16x16x32_bf16 v[86:89], v[128:131], v[98:101], v[44:47]
	v_mfma_f32_16x16x32_bf16 v[98:101], v[128:131], v[120:123], v[28:31]
	v_mfma_f32_16x16x32_bf16 v[144:147], v[132:135], v[120:123], v[24:27]
	v_mfma_f32_16x16x32_bf16 v[120:123], v[128:131], v[124:127], v[12:15]
	v_mfma_f32_16x16x32_bf16 v[128:131], v[132:135], v[124:127], v[8:11]
	v_mfma_f32_16x16x32_bf16 v[132:135], v[136:139], v[124:127], v[4:7]
	s_setprio 0
	s_nop 1
	ds_read_b128 v[4:7], v94 offset:16384
	ds_read_b128 v[8:11], v94 offset:18432
	ds_read_b128 v[124:127], v94 offset:20480
	ds_read_b128 v[136:139], v94 offset:22528
	ds_read_b128 v[140:143], v95 offset:49152
	ds_read_b128 v[148:151], v95 offset:51200
	ds_read_b128 v[152:155], v95 offset:53248
	ds_read_b128 v[156:159], v95 offset:55296
	s_setprio 1
	s_waitcnt lgkmcnt(3)
	v_mfma_f32_16x16x32_bf16 v[60:63], v[140:143], v[4:7], v[60:63]
	s_waitcnt lgkmcnt(2)
	v_mfma_f32_16x16x32_bf16 v[44:47], v[148:151], v[4:7], v[56:59]
	s_waitcnt lgkmcnt(1)
	v_mfma_f32_16x16x32_bf16 v[28:31], v[152:155], v[4:7], v[52:55]
	s_waitcnt lgkmcnt(0)
	v_mfma_f32_16x16x32_bf16 v[12:15], v[156:159], v[4:7], v[48:51]
	v_mfma_f32_16x16x32_bf16 v[56:59], v[140:143], v[8:11], v[86:89]
	v_mfma_f32_16x16x32_bf16 v[40:43], v[148:151], v[8:11], v[40:43]
	v_mfma_f32_16x16x32_bf16 v[24:27], v[152:155], v[8:11], v[36:39]
	v_mfma_f32_16x16x32_bf16 v[8:11], v[156:159], v[8:11], v[32:35]
	v_mfma_f32_16x16x32_bf16 v[52:55], v[140:143], v[124:127], v[98:101]
	v_mfma_f32_16x16x32_bf16 v[36:39], v[148:151], v[124:127], v[144:147]
	v_mfma_f32_16x16x32_bf16 v[20:23], v[152:155], v[124:127], v[20:23]
	v_mfma_f32_16x16x32_bf16 v[4:7], v[156:159], v[124:127], v[16:19]
	v_mfma_f32_16x16x32_bf16 v[48:51], v[140:143], v[136:139], v[120:123]
	v_mfma_f32_16x16x32_bf16 v[32:35], v[148:151], v[136:139], v[128:131]
	v_mfma_f32_16x16x32_bf16 v[16:19], v[152:155], v[136:139], v[132:135]
	v_mfma_f32_16x16x32_bf16 v[0:3], v[156:159], v[136:139], v[0:3]
	s_setprio 2
	s_waitcnt vmcnt(0)
	s_cmpk_gt_i32 s1, 0x7f
	s_barrier
	s_cbranch_scc0 .LBB0_885
	s_add_i32 s0, s24, 0xffffc000
	s_lshr_b32 s0, s0, 8
	v_readlane_b32 s6, v180, 24
	s_add_i32 s6, s0, s6
	s_and_b32 s10, s24, 0x80
	s_lshl_b64 s[8:9], s[6:7], 8
	v_readlane_b32 s36, v182, 19
	s_or_b32 s8, s8, s10
	s_mov_b64 s[10:11], 0
	v_readlane_b32 s37, v182, 20
	s_branch .LBB0_886

.LBB0_895:
	s_setprio 3
	s_and_b32 s0, s10, 0x2000
	s_xor_b32 s1, s0, 0x2000
	s_lshl_b32 s101, s1, 1
	s_add_u32 s101, s101, s100
	s_add_u32 m0, s101, 0x0
	s_nop 0
	global_load_lds_dwordx4 v[184:185], off
	s_add_u32 m0, s101, 0x1000
	v_lshl_add_u64 v[184:185], v[184:185], 0, vcc
	global_load_lds_dwordx4 v[186:187], off
	s_add_u32 m0, s101, 0x2000
	v_lshl_add_u64 v[186:187], v[186:187], 0, vcc
	global_load_lds_dwordx4 v[188:189], off
	s_add_u32 m0, s101, 0x3000
	v_lshl_add_u64 v[188:189], v[188:189], 0, vcc
	global_load_lds_dwordx4 v[190:191], off
	s_add_u32 m0, s101, 0x8000
	v_lshl_add_u64 v[190:191], v[190:191], 0, vcc
	global_load_lds_dwordx4 v[192:193], off
	s_add_u32 m0, s101, 0x9000
	v_lshl_add_u64 v[192:193], v[192:193], 0, vcc
	global_load_lds_dwordx4 v[194:195], off
	s_add_u32 m0, s101, 0xa000
	v_lshl_add_u64 v[194:195], v[194:195], 0, vcc
	global_load_lds_dwordx4 v[196:197], off
	s_add_u32 m0, s101, 0xb000
	v_lshl_add_u64 v[196:197], v[196:197], 0, vcc
	global_load_lds_dwordx4 v[198:199], off
	v_lshl_add_u64 v[198:199], v[198:199], 0, vcc
	s_lshl_b32 s0, s0, 1
	v_add_u32_e32 v68, s0, v120
	v_add_u32_e32 v102, s0, v121
	v_add_u32_e32 v98, v68, v133
	v_add_u32_e32 v103, v102, v133
	ds_read_b128 v[86:89], v98
	ds_read_b128 v[90:93], v98 offset:2048
	ds_read_b128 v[94:97], v98 offset:4096
	ds_read_b128 v[98:101], v98 offset:6144
	ds_read_b128 v[144:147], v103 offset:32768
	ds_read_b128 v[148:151], v103 offset:34816
	ds_read_b128 v[152:155], v103 offset:36864
	ds_read_b128 v[156:159], v103 offset:38912
	s_setprio 1
	s_waitcnt lgkmcnt(0)
	v_mfma_f32_16x16x32_bf16 v[60:63], v[86:89], v[144:147], v[60:63]
	v_mfma_f32_16x16x32_bf16 v[56:59], v[86:89], v[148:151], v[56:59]
	v_mfma_f32_16x16x32_bf16 v[52:55], v[86:89], v[152:155], v[52:55]
	v_mfma_f32_16x16x32_bf16 v[48:51], v[86:89], v[156:159], v[48:51]
	v_mfma_f32_16x16x32_bf16 v[44:47], v[90:93], v[144:147], v[44:47]
	v_mfma_f32_16x16x32_bf16 v[40:43], v[90:93], v[148:151], v[40:43]
	v_mfma_f32_16x16x32_bf16 v[36:39], v[90:93], v[152:155], v[36:39]
	v_mfma_f32_16x16x32_bf16 v[32:35], v[90:93], v[156:159], v[32:35]
	v_mfma_f32_16x16x32_bf16 v[28:31], v[94:97], v[144:147], v[28:31]
	v_mfma_f32_16x16x32_bf16 v[24:27], v[94:97], v[148:151], v[24:27]
	v_mfma_f32_16x16x32_bf16 v[20:23], v[94:97], v[152:155], v[20:23]
	v_mfma_f32_16x16x32_bf16 v[16:19], v[94:97], v[156:159], v[16:19]
	v_mfma_f32_16x16x32_bf16 v[12:15], v[98:101], v[144:147], v[12:15]
	v_mfma_f32_16x16x32_bf16 v[8:11], v[98:101], v[148:151], v[8:11]
	v_mfma_f32_16x16x32_bf16 v[4:7], v[98:101], v[152:155], v[4:7]
	v_mfma_f32_16x16x32_bf16 v[0:3], v[98:101], v[156:159], v[0:3]
	s_setprio 0
	v_add_u32_e32 v68, v68, v134
	ds_read_b128 v[86:89], v68
	ds_read_b128 v[90:93], v68 offset:2048
	ds_read_b128 v[94:97], v68 offset:4096
	ds_read_b128 v[98:101], v68 offset:6144
	v_add_u32_e32 v68, v102, v134
	ds_read_b128 v[144:147], v68 offset:32768
	ds_read_b128 v[148:151], v68 offset:34816
	ds_read_b128 v[152:155], v68 offset:36864
	ds_read_b128 v[156:159], v68 offset:38912
	s_setprio 1
	s_waitcnt lgkmcnt(0)
	v_mfma_f32_16x16x32_bf16 v[60:63], v[86:89], v[144:147], v[60:63]
	v_mfma_f32_16x16x32_bf16 v[56:59], v[86:89], v[148:151], v[56:59]
	v_mfma_f32_16x16x32_bf16 v[52:55], v[86:89], v[152:155], v[52:55]
	v_mfma_f32_16x16x32_bf16 v[48:51], v[86:89], v[156:159], v[48:51]
	v_mfma_f32_16x16x32_bf16 v[44:47], v[90:93], v[144:147], v[44:47]
	v_mfma_f32_16x16x32_bf16 v[40:43], v[90:93], v[148:151], v[40:43]
	v_mfma_f32_16x16x32_bf16 v[36:39], v[90:93], v[152:155], v[36:39]
	v_mfma_f32_16x16x32_bf16 v[32:35], v[90:93], v[156:159], v[32:35]
	v_mfma_f32_16x16x32_bf16 v[28:31], v[94:97], v[144:147], v[28:31]
	v_mfma_f32_16x16x32_bf16 v[24:27], v[94:97], v[148:151], v[24:27]
	v_mfma_f32_16x16x32_bf16 v[20:23], v[94:97], v[152:155], v[20:23]
	v_mfma_f32_16x16x32_bf16 v[16:19], v[94:97], v[156:159], v[16:19]
	v_mfma_f32_16x16x32_bf16 v[12:15], v[98:101], v[144:147], v[12:15]
	v_mfma_f32_16x16x32_bf16 v[8:11], v[98:101], v[148:151], v[8:11]
	v_mfma_f32_16x16x32_bf16 v[4:7], v[98:101], v[152:155], v[4:7]
	v_mfma_f32_16x16x32_bf16 v[0:3], v[98:101], v[156:159], v[0:3]
	s_setprio 0
	s_addk_i32 s10, 0x2000
	s_waitcnt vmcnt(0)
	s_add_u32 s36, s36, 0x80
	s_addc_u32 s37, s37, 0
	s_cmpk_lg_i32 s36, 0x780
	s_waitcnt vmcnt(0)
	s_barrier
	s_cbranch_scc1 .LBB0_895
	ds_read_b128 v[82:85], v122 offset:55296
	ds_read_b128 v[86:89], v122 offset:53248
	ds_read_b128 v[90:93], v122 offset:51200
	ds_read_b128 v[94:97], v122 offset:49152
	ds_read_b128 v[98:101], v123 offset:22528
	ds_read_b128 v[144:147], v123 offset:20480
	ds_read_b128 v[148:151], v123 offset:18432
	ds_read_b128 v[152:155], v123 offset:16384
	s_setprio 1
	s_waitcnt lgkmcnt(0)
	v_mfma_f32_16x16x32_bf16 v[60:63], v[152:155], v[94:97], v[60:63]
	v_mfma_f32_16x16x32_bf16 v[52:55], v[152:155], v[86:89], v[52:55]
	v_mfma_f32_16x16x32_bf16 v[48:51], v[152:155], v[82:85], v[48:51]
	v_mfma_f32_16x16x32_bf16 v[44:47], v[148:151], v[94:97], v[44:47]
	v_mfma_f32_16x16x32_bf16 v[40:43], v[148:151], v[90:93], v[40:43]
	v_mfma_f32_16x16x32_bf16 v[36:39], v[148:151], v[86:89], v[36:39]
	v_mfma_f32_16x16x32_bf16 v[32:35], v[148:151], v[82:85], v[32:35]
	v_mfma_f32_16x16x32_bf16 v[4:7], v[98:101], v[86:89], v[4:7]
	v_mfma_f32_16x16x32_bf16 v[156:159], v[152:155], v[90:93], v[56:59]
	v_mfma_f32_16x16x32_bf16 v[148:151], v[144:147], v[94:97], v[28:31]
	v_mfma_f32_16x16x32_bf16 v[152:155], v[144:147], v[90:93], v[24:27]
	v_mfma_f32_16x16x32_bf16 v[160:163], v[144:147], v[86:89], v[20:23]
	v_mfma_f32_16x16x32_bf16 v[144:147], v[144:147], v[82:85], v[16:19]
	v_mfma_f32_16x16x32_bf16 v[94:97], v[98:101], v[94:97], v[12:15]
	v_mfma_f32_16x16x32_bf16 v[90:93], v[98:101], v[90:93], v[8:11]
	v_mfma_f32_16x16x32_bf16 v[82:85], v[98:101], v[82:85], v[0:3]
	s_setprio 0
	s_nop 1
	ds_read_b128 v[0:3], v124 offset:16384
	ds_read_b128 v[8:11], v124 offset:18432
	ds_read_b128 v[12:15], v124 offset:20480
	ds_read_b128 v[86:89], v124 offset:22528
	ds_read_b128 v[98:101], v125 offset:49152
	ds_read_b128 v[164:167], v125 offset:51200
	ds_read_b128 v[168:171], v125 offset:53248
	ds_read_b128 v[172:175], v125 offset:55296
	s_setprio 1
	s_waitcnt lgkmcnt(3)
	v_mfma_f32_16x16x32_bf16 v[56:59], v[0:3], v[98:101], v[60:63]
	s_waitcnt lgkmcnt(2)
	v_mfma_f32_16x16x32_bf16 v[60:63], v[0:3], v[164:167], v[156:159]
	s_waitcnt lgkmcnt(1)
	v_mfma_f32_16x16x32_bf16 v[24:27], v[0:3], v[168:171], v[52:55]
	s_waitcnt lgkmcnt(0)
	v_mfma_f32_16x16x32_bf16 v[28:31], v[0:3], v[172:175], v[48:51]
	v_mfma_f32_16x16x32_bf16 v[52:55], v[8:11], v[98:101], v[44:47]
	v_mfma_f32_16x16x32_bf16 v[48:51], v[8:11], v[164:167], v[40:43]
	v_mfma_f32_16x16x32_bf16 v[16:19], v[8:11], v[168:171], v[36:39]
	v_mfma_f32_16x16x32_bf16 v[20:23], v[8:11], v[172:175], v[32:35]
	v_mfma_f32_16x16x32_bf16 v[40:43], v[12:15], v[98:101], v[148:151]
	v_mfma_f32_16x16x32_bf16 v[44:47], v[12:15], v[164:167], v[152:155]
	v_mfma_f32_16x16x32_bf16 v[8:11], v[12:15], v[168:171], v[160:163]
	v_mfma_f32_16x16x32_bf16 v[12:15], v[12:15], v[172:175], v[144:147]
	v_mfma_f32_16x16x32_bf16 v[32:35], v[86:89], v[98:101], v[94:97]
	v_mfma_f32_16x16x32_bf16 v[36:39], v[86:89], v[164:167], v[90:93]
	v_mfma_f32_16x16x32_bf16 v[0:3], v[86:89], v[168:171], v[4:7]
	v_mfma_f32_16x16x32_bf16 v[4:7], v[86:89], v[172:175], v[82:85]
	s_setprio 2
	s_waitcnt vmcnt(0)
	s_cmpk_lt_i32 s9, 0x80
	s_cselect_b64 s[42:43], -1, 0
	s_cmpk_gt_i32 s9, 0x7f
	s_mov_b64 s[0:1], -1
	s_barrier
	s_cbranch_scc0 .LBB0_904
	s_and_b32 s10, s20, 0x80
	s_cbranch_execz .LBB0_905

.LBB0_1239:
	s_setprio 3
	s_and_b32 s9, s8, 0x2000
	s_xor_b32 s18, s9, 0x2000
	s_lshl_b32 s101, s18, 1
	s_add_u32 s101, s101, s100
	s_add_u32 m0, s101, 0x0
	s_nop 0
	global_load_lds_dwordx4 v[184:185], off
	s_add_u32 m0, s101, 0x1000
	v_lshl_add_u64 v[184:185], v[184:185], 0, vcc
	global_load_lds_dwordx4 v[186:187], off
	s_add_u32 m0, s101, 0x2000
	v_lshl_add_u64 v[186:187], v[186:187], 0, vcc
	global_load_lds_dwordx4 v[188:189], off
	s_add_u32 m0, s101, 0x3000
	v_lshl_add_u64 v[188:189], v[188:189], 0, vcc
	global_load_lds_dwordx4 v[190:191], off
	s_add_u32 m0, s101, 0x8000
	v_lshl_add_u64 v[190:191], v[190:191], 0, vcc
	global_load_lds_dwordx4 v[192:193], off
	s_add_u32 m0, s101, 0x9000
	v_lshl_add_u64 v[192:193], v[192:193], 0, vcc
	global_load_lds_dwordx4 v[194:195], off
	s_add_u32 m0, s101, 0xa000
	v_lshl_add_u64 v[194:195], v[194:195], 0, vcc
	global_load_lds_dwordx4 v[196:197], off
	s_add_u32 m0, s101, 0xb000
	v_lshl_add_u64 v[196:197], v[196:197], 0, vcc
	global_load_lds_dwordx4 v[198:199], off
	v_lshl_add_u64 v[198:199], v[198:199], 0, vcc
	s_lshl_b32 s9, s9, 1
	v_add_u32_e32 v136, s9, v84
	v_add_u32_e32 v137, s9, v83
	v_add_u32_e32 v100, v136, v86
	v_add_u32_e32 v132, v137, v86
	ds_read_b128 v[88:91], v100
	ds_read_b128 v[92:95], v100 offset:2048
	ds_read_b128 v[96:99], v100 offset:4096
	ds_read_b128 v[100:103], v100 offset:6144
	ds_read_b128 v[120:123], v132 offset:32768
	ds_read_b128 v[124:127], v132 offset:34816
	ds_read_b128 v[128:131], v132 offset:36864
	ds_read_b128 v[132:135], v132 offset:38912
	s_setprio 1
	s_waitcnt lgkmcnt(0)
	v_mfma_f32_16x16x32_bf16 v[60:63], v[120:123], v[88:91], v[60:63]
	v_mfma_f32_16x16x32_bf16 v[56:59], v[124:127], v[88:91], v[56:59]
	v_mfma_f32_16x16x32_bf16 v[52:55], v[128:131], v[88:91], v[52:55]
	v_mfma_f32_16x16x32_bf16 v[48:51], v[132:135], v[88:91], v[48:51]
	v_mfma_f32_16x16x32_bf16 v[44:47], v[120:123], v[92:95], v[44:47]
	v_mfma_f32_16x16x32_bf16 v[40:43], v[124:127], v[92:95], v[40:43]
	v_mfma_f32_16x16x32_bf16 v[36:39], v[128:131], v[92:95], v[36:39]
	v_mfma_f32_16x16x32_bf16 v[32:35], v[132:135], v[92:95], v[32:35]
	v_mfma_f32_16x16x32_bf16 v[28:31], v[120:123], v[96:99], v[28:31]
	v_mfma_f32_16x16x32_bf16 v[24:27], v[124:127], v[96:99], v[24:27]
	v_mfma_f32_16x16x32_bf16 v[20:23], v[128:131], v[96:99], v[20:23]
	v_mfma_f32_16x16x32_bf16 v[16:19], v[132:135], v[96:99], v[16:19]
	v_mfma_f32_16x16x32_bf16 v[12:15], v[120:123], v[100:103], v[12:15]
	v_mfma_f32_16x16x32_bf16 v[8:11], v[124:127], v[100:103], v[8:11]
	v_mfma_f32_16x16x32_bf16 v[4:7], v[128:131], v[100:103], v[4:7]
	v_mfma_f32_16x16x32_bf16 v[0:3], v[132:135], v[100:103], v[0:3]
	s_setprio 0
	v_add_u32_e32 v100, v136, v87
	v_add_u32_e32 v132, v137, v87
	ds_read_b128 v[88:91], v100
	ds_read_b128 v[92:95], v100 offset:2048
	ds_read_b128 v[96:99], v100 offset:4096
	ds_read_b128 v[100:103], v100 offset:6144
	ds_read_b128 v[120:123], v132 offset:32768
	ds_read_b128 v[124:127], v132 offset:34816
	ds_read_b128 v[128:131], v132 offset:36864
	ds_read_b128 v[132:135], v132 offset:38912
	s_setprio 1
	s_waitcnt lgkmcnt(0)
	v_mfma_f32_16x16x32_bf16 v[60:63], v[120:123], v[88:91], v[60:63]
	v_mfma_f32_16x16x32_bf16 v[56:59], v[124:127], v[88:91], v[56:59]
	v_mfma_f32_16x16x32_bf16 v[52:55], v[128:131], v[88:91], v[52:55]
	v_mfma_f32_16x16x32_bf16 v[48:51], v[132:135], v[88:91], v[48:51]
	v_mfma_f32_16x16x32_bf16 v[44:47], v[120:123], v[92:95], v[44:47]
	v_mfma_f32_16x16x32_bf16 v[40:43], v[124:127], v[92:95], v[40:43]
	v_mfma_f32_16x16x32_bf16 v[36:39], v[128:131], v[92:95], v[36:39]
	v_mfma_f32_16x16x32_bf16 v[32:35], v[132:135], v[92:95], v[32:35]
	v_mfma_f32_16x16x32_bf16 v[28:31], v[120:123], v[96:99], v[28:31]
	v_mfma_f32_16x16x32_bf16 v[24:27], v[124:127], v[96:99], v[24:27]
	v_mfma_f32_16x16x32_bf16 v[20:23], v[128:131], v[96:99], v[20:23]
	v_mfma_f32_16x16x32_bf16 v[16:19], v[132:135], v[96:99], v[16:19]
	v_mfma_f32_16x16x32_bf16 v[12:15], v[120:123], v[100:103], v[12:15]
	v_mfma_f32_16x16x32_bf16 v[8:11], v[124:127], v[100:103], v[8:11]
	v_mfma_f32_16x16x32_bf16 v[4:7], v[128:131], v[100:103], v[4:7]
	v_mfma_f32_16x16x32_bf16 v[0:3], v[132:135], v[100:103], v[0:3]
	s_setprio 0
	s_waitcnt vmcnt(0)
	s_add_u32 s20, s20, 0x80
	s_addc_u32 s21, s21, 0
	s_addk_i32 s8, 0x2000
	s_cmp_lg_u32 s1, s20
	s_waitcnt vmcnt(0)
	s_barrier
	s_cbranch_scc1 .LBB0_1239
	s_lshl_b32 s1, s36, 14
	s_addk_i32 s1, 0x4000
	s_and_b32 s1, s1, 0x4000
	v_add_u32_e32 v132, s1, v84
	v_add_u32_e32 v133, s1, v83
	v_add_u32_e32 v96, v132, v86
	v_add_u32_e32 v128, v133, v86
	ds_read_b128 v[78:81], v96
	ds_read_b128 v[88:91], v96 offset:2048
	ds_read_b128 v[92:95], v96 offset:4096
	ds_read_b128 v[96:99], v96 offset:6144
	ds_read_b128 v[100:103], v128 offset:32768
	ds_read_b128 v[120:123], v128 offset:34816
	ds_read_b128 v[124:127], v128 offset:36864
	ds_read_b128 v[128:131], v128 offset:38912
	s_setprio 1
	s_waitcnt lgkmcnt(3)
	v_mfma_f32_16x16x32_bf16 v[60:63], v[100:103], v[78:81], v[60:63]
	s_waitcnt lgkmcnt(2)
	v_mfma_f32_16x16x32_bf16 v[56:59], v[120:123], v[78:81], v[56:59]
	s_waitcnt lgkmcnt(1)
	v_mfma_f32_16x16x32_bf16 v[52:55], v[124:127], v[78:81], v[52:55]
	s_waitcnt lgkmcnt(0)
	v_mfma_f32_16x16x32_bf16 v[48:51], v[128:131], v[78:81], v[48:51]
	v_mfma_f32_16x16x32_bf16 v[44:47], v[100:103], v[88:91], v[44:47]
	v_mfma_f32_16x16x32_bf16 v[40:43], v[120:123], v[88:91], v[40:43]
	v_mfma_f32_16x16x32_bf16 v[36:39], v[124:127], v[88:91], v[36:39]
	v_mfma_f32_16x16x32_bf16 v[32:35], v[128:131], v[88:91], v[32:35]
	v_mfma_f32_16x16x32_bf16 v[28:31], v[100:103], v[92:95], v[28:31]
	v_mfma_f32_16x16x32_bf16 v[24:27], v[120:123], v[92:95], v[24:27]
	v_mfma_f32_16x16x32_bf16 v[20:23], v[124:127], v[92:95], v[20:23]
	v_mfma_f32_16x16x32_bf16 v[16:19], v[128:131], v[92:95], v[16:19]
	v_mfma_f32_16x16x32_bf16 v[12:15], v[100:103], v[96:99], v[12:15]
	v_mfma_f32_16x16x32_bf16 v[8:11], v[120:123], v[96:99], v[8:11]
	v_mfma_f32_16x16x32_bf16 v[4:7], v[124:127], v[96:99], v[4:7]
	v_mfma_f32_16x16x32_bf16 v[0:3], v[128:131], v[96:99], v[0:3]
	s_setprio 0
	v_add_u32_e32 v96, v132, v87
	v_add_u32_e32 v128, v133, v87
	ds_read_b128 v[78:81], v96
	ds_read_b128 v[88:91], v96 offset:2048
	ds_read_b128 v[92:95], v96 offset:4096
	ds_read_b128 v[96:99], v96 offset:6144
	ds_read_b128 v[100:103], v128 offset:32768
	ds_read_b128 v[120:123], v128 offset:34816
	ds_read_b128 v[124:127], v128 offset:36864
	ds_read_b128 v[128:131], v128 offset:38912
	s_setprio 1
	s_waitcnt lgkmcnt(3)
	v_mfma_f32_16x16x32_bf16 v[60:63], v[100:103], v[78:81], v[60:63]
	s_waitcnt lgkmcnt(2)
	v_mfma_f32_16x16x32_bf16 v[56:59], v[120:123], v[78:81], v[56:59]
	s_waitcnt lgkmcnt(1)
	v_mfma_f32_16x16x32_bf16 v[52:55], v[124:127], v[78:81], v[52:55]
	s_waitcnt lgkmcnt(0)
	v_mfma_f32_16x16x32_bf16 v[48:51], v[128:131], v[78:81], v[48:51]
	v_mfma_f32_16x16x32_bf16 v[44:47], v[100:103], v[88:91], v[44:47]
	v_mfma_f32_16x16x32_bf16 v[40:43], v[120:123], v[88:91], v[40:43]
	v_mfma_f32_16x16x32_bf16 v[36:39], v[124:127], v[88:91], v[36:39]
	v_mfma_f32_16x16x32_bf16 v[32:35], v[128:131], v[88:91], v[32:35]
	v_mfma_f32_16x16x32_bf16 v[28:31], v[100:103], v[92:95], v[28:31]
	v_mfma_f32_16x16x32_bf16 v[24:27], v[120:123], v[92:95], v[24:27]
	v_mfma_f32_16x16x32_bf16 v[20:23], v[124:127], v[92:95], v[20:23]
	v_mfma_f32_16x16x32_bf16 v[16:19], v[128:131], v[92:95], v[16:19]
	v_mfma_f32_16x16x32_bf16 v[12:15], v[100:103], v[96:99], v[12:15]
	v_mfma_f32_16x16x32_bf16 v[8:11], v[120:123], v[96:99], v[8:11]
	v_mfma_f32_16x16x32_bf16 v[4:7], v[124:127], v[96:99], v[4:7]
	v_mfma_f32_16x16x32_bf16 v[0:3], v[128:131], v[96:99], v[0:3]
	s_setprio 2
	s_lshl_b32 s1, s25, 3
	s_lshl_b32 s8, s11, 1
	s_or_b32 s1, s8, s1
	s_or_b32 s1, s1, s13
	s_lshl_b32 s1, s1, 4
	s_or_b32 s8, s1, s24
	s_ashr_i32 s9, s8, 31
	s_lshl_b64 s[8:9], s[8:9], 18
	s_add_u32 s8, s52, s8
	v_add_lshl_u32 v78, s10, v71, 8
	s_addc_u32 s9, s53, s9
	v_or_b32_e32 v80, s0, v85
	v_ashrrev_i32_e32 v79, 31, v78
	v_lshl_add_u64 v[78:79], v[78:79], 1, s[8:9]
	v_cvt_pk_bf16_f32 v60, v60, v61
	v_cvt_pk_bf16_f32 v61, v62, v63
	v_lshlrev_b32_e32 v62, 1, v80
	v_mov_b32_e32 v63, v69
	v_lshl_add_u64 v[80:81], v[78:79], 0, v[62:63]
	v_cvt_pk_bf16_f32 v48, v48, v49
	v_cvt_pk_bf16_f32 v49, v50, v51
	s_mov_b64 s[0:1], 0x2000
	s_waitcnt vmcnt(0)
	s_barrier
	global_store_dwordx2 v[80:81], v[48:49], off offset:96
	v_lshl_add_u64 v[48:49], v[78:79], 0, s[0:1]
	v_cvt_pk_bf16_f32 v44, v44, v45
	v_cvt_pk_bf16_f32 v45, v46, v47
	v_lshl_add_u64 v[46:47], v[48:49], 0, v[62:63]
	v_cvt_pk_bf16_f32 v40, v40, v41
	v_cvt_pk_bf16_f32 v41, v42, v43
	v_or_b32_e32 v42, 32, v62
	v_mov_b32_e32 v43, v69
	global_store_dwordx2 v[46:47], v[44:45], off
	v_lshl_add_u64 v[44:45], v[48:49], 0, v[42:43]
	v_cvt_pk_bf16_f32 v36, v36, v37
	v_cvt_pk_bf16_f32 v37, v38, v39
	v_or_b32_e32 v38, 64, v62
	v_mov_b32_e32 v39, v69
	global_store_dwordx2 v[44:45], v[40:41], off
	v_lshl_add_u64 v[40:41], v[48:49], 0, v[38:39]
	v_cvt_pk_bf16_f32 v32, v32, v33
	v_cvt_pk_bf16_f32 v33, v34, v35
	v_or_b32_e32 v34, 0x60, v62
	v_mov_b32_e32 v35, v69
	global_store_dwordx2 v[40:41], v[36:37], off
	v_lshl_add_u64 v[36:37], v[48:49], 0, v[34:35]
	s_mov_b64 s[0:1], 0x4000
	global_store_dwordx2 v[36:37], v[32:33], off
	v_lshl_add_u64 v[32:33], v[78:79], 0, s[0:1]
	v_cvt_pk_bf16_f32 v16, v16, v17
	v_cvt_pk_bf16_f32 v17, v18, v19
	v_lshl_add_u64 v[18:19], v[32:33], 0, v[34:35]
	s_mov_b64 s[0:1], 0x6000
	global_store_dwordx2 v[18:19], v[16:17], off
	v_lshl_add_u64 v[16:17], v[78:79], 0, s[0:1]
	v_readlane_b32 s0, v181, 50
	s_add_i32 s6, s6, s84
	s_add_i32 s12, s12, s0
	v_cvt_pk_bf16_f32 v56, v56, v57
	v_cvt_pk_bf16_f32 v57, v58, v59
	v_cvt_pk_bf16_f32 v52, v52, v53
	v_cvt_pk_bf16_f32 v53, v54, v55
	v_cvt_pk_bf16_f32 v28, v28, v29
	v_cvt_pk_bf16_f32 v29, v30, v31
	v_lshl_add_u64 v[30:31], v[32:33], 0, v[62:63]
	v_cvt_pk_bf16_f32 v24, v24, v25
	v_cvt_pk_bf16_f32 v25, v26, v27
	v_lshl_add_u64 v[26:27], v[32:33], 0, v[42:43]
	v_cvt_pk_bf16_f32 v20, v20, v21
	v_cvt_pk_bf16_f32 v21, v22, v23
	v_lshl_add_u64 v[22:23], v[32:33], 0, v[38:39]
	v_cvt_pk_bf16_f32 v12, v12, v13
	v_cvt_pk_bf16_f32 v13, v14, v15
	v_lshl_add_u64 v[14:15], v[16:17], 0, v[62:63]
	v_cvt_pk_bf16_f32 v8, v8, v9
	v_cvt_pk_bf16_f32 v9, v10, v11
	v_lshl_add_u64 v[10:11], v[16:17], 0, v[42:43]
	v_cvt_pk_bf16_f32 v4, v4, v5
	v_cvt_pk_bf16_f32 v5, v6, v7
	v_lshl_add_u64 v[6:7], v[16:17], 0, v[38:39]
	v_cvt_pk_bf16_f32 v0, v0, v1
	v_cvt_pk_bf16_f32 v1, v2, v3
	v_lshl_add_u64 v[2:3], v[16:17], 0, v[34:35]
	s_cmpk_lt_i32 s6, 0x800
	global_store_dwordx2 v[80:81], v[60:61], off
	global_store_dwordx2 v[80:81], v[56:57], off offset:32
	global_store_dwordx2 v[80:81], v[52:53], off offset:64
	global_store_dwordx2 v[30:31], v[28:29], off
	global_store_dwordx2 v[26:27], v[24:25], off
	global_store_dwordx2 v[22:23], v[20:21], off
	global_store_dwordx2 v[14:15], v[12:13], off
	global_store_dwordx2 v[10:11], v[8:9], off
	global_store_dwordx2 v[6:7], v[4:5], off
	global_store_dwordx2 v[2:3], v[0:1], off
	s_cbranch_scc1 .LBB0_1234
	v_readlane_b32 s50, v180, 0
	s_mov_b32 s18, 0x42ce8ed0
	s_mov_b32 s19, 0xc2b17218
	s_mov_b32 s48, s5
	v_readlane_b32 s51, v180, 1

.LBB0_1487:
	s_setprio 3
	s_and_b32 s6, s0, 0x2000
	s_xor_b32 s8, s6, 0x2000
	s_lshl_b32 s101, s8, 1
	s_add_u32 s101, s101, s100
	s_add_u32 m0, s101, 0x0
	s_nop 0
	global_load_lds_dwordx4 v[184:185], off
	s_add_u32 m0, s101, 0x1000
	v_lshl_add_u64 v[184:185], v[184:185], 0, vcc
	global_load_lds_dwordx4 v[186:187], off
	s_add_u32 m0, s101, 0x2000
	v_lshl_add_u64 v[186:187], v[186:187], 0, vcc
	global_load_lds_dwordx4 v[188:189], off
	s_add_u32 m0, s101, 0x3000
	v_lshl_add_u64 v[188:189], v[188:189], 0, vcc
	global_load_lds_dwordx4 v[190:191], off
	s_add_u32 m0, s101, 0x8000
	v_lshl_add_u64 v[190:191], v[190:191], 0, vcc
	global_load_lds_dwordx4 v[192:193], off
	s_add_u32 m0, s101, 0x9000
	v_lshl_add_u64 v[192:193], v[192:193], 0, vcc
	global_load_lds_dwordx4 v[194:195], off
	s_add_u32 m0, s101, 0xa000
	v_lshl_add_u64 v[194:195], v[194:195], 0, vcc
	global_load_lds_dwordx4 v[196:197], off
	s_add_u32 m0, s101, 0xb000
	v_lshl_add_u64 v[196:197], v[196:197], 0, vcc
	global_load_lds_dwordx4 v[198:199], off
	v_lshl_add_u64 v[198:199], v[198:199], 0, vcc
	s_lshl_b32 s6, s6, 1
	v_add_u32_e32 v148, s6, v92
	v_add_u32_e32 v149, s6, v71
	v_add_u32_e32 v128, v148, v98
	v_add_u32_e32 v144, v149, v98
	ds_read_b128 v[100:103], v128
	ds_read_b128 v[120:123], v128 offset:2048
	ds_read_b128 v[124:127], v128 offset:4096
	ds_read_b128 v[128:131], v128 offset:6144
	ds_read_b128 v[132:135], v144 offset:32768
	ds_read_b128 v[136:139], v144 offset:34816
	ds_read_b128 v[140:143], v144 offset:36864
	ds_read_b128 v[144:147], v144 offset:38912
	s_setprio 1
	s_waitcnt lgkmcnt(0)
	v_mfma_f32_16x16x32_bf16 v[60:63], v[132:135], v[100:103], v[60:63]
	v_mfma_f32_16x16x32_bf16 v[56:59], v[136:139], v[100:103], v[56:59]
	v_mfma_f32_16x16x32_bf16 v[52:55], v[140:143], v[100:103], v[52:55]
	v_mfma_f32_16x16x32_bf16 v[48:51], v[144:147], v[100:103], v[48:51]
	v_mfma_f32_16x16x32_bf16 v[44:47], v[132:135], v[120:123], v[44:47]
	v_mfma_f32_16x16x32_bf16 v[40:43], v[136:139], v[120:123], v[40:43]
	v_mfma_f32_16x16x32_bf16 v[36:39], v[140:143], v[120:123], v[36:39]
	v_mfma_f32_16x16x32_bf16 v[32:35], v[144:147], v[120:123], v[32:35]
	v_mfma_f32_16x16x32_bf16 v[28:31], v[132:135], v[124:127], v[28:31]
	v_mfma_f32_16x16x32_bf16 v[24:27], v[136:139], v[124:127], v[24:27]
	v_mfma_f32_16x16x32_bf16 v[20:23], v[140:143], v[124:127], v[20:23]
	v_mfma_f32_16x16x32_bf16 v[16:19], v[144:147], v[124:127], v[16:19]
	v_mfma_f32_16x16x32_bf16 v[12:15], v[132:135], v[128:131], v[12:15]
	v_mfma_f32_16x16x32_bf16 v[8:11], v[136:139], v[128:131], v[8:11]
	v_mfma_f32_16x16x32_bf16 v[4:7], v[140:143], v[128:131], v[4:7]
	v_mfma_f32_16x16x32_bf16 v[0:3], v[144:147], v[128:131], v[0:3]
	s_setprio 0
	v_add_u32_e32 v128, v148, v99
	v_add_u32_e32 v144, v149, v99
	ds_read_b128 v[100:103], v128
	ds_read_b128 v[120:123], v128 offset:2048
	ds_read_b128 v[124:127], v128 offset:4096
	ds_read_b128 v[128:131], v128 offset:6144
	ds_read_b128 v[132:135], v144 offset:32768
	ds_read_b128 v[136:139], v144 offset:34816
	ds_read_b128 v[140:143], v144 offset:36864
	ds_read_b128 v[144:147], v144 offset:38912
	s_setprio 1
	s_waitcnt lgkmcnt(0)
	v_mfma_f32_16x16x32_bf16 v[60:63], v[132:135], v[100:103], v[60:63]
	v_mfma_f32_16x16x32_bf16 v[56:59], v[136:139], v[100:103], v[56:59]
	v_mfma_f32_16x16x32_bf16 v[52:55], v[140:143], v[100:103], v[52:55]
	v_mfma_f32_16x16x32_bf16 v[48:51], v[144:147], v[100:103], v[48:51]
	v_mfma_f32_16x16x32_bf16 v[44:47], v[132:135], v[120:123], v[44:47]
	v_mfma_f32_16x16x32_bf16 v[40:43], v[136:139], v[120:123], v[40:43]
	v_mfma_f32_16x16x32_bf16 v[36:39], v[140:143], v[120:123], v[36:39]
	v_mfma_f32_16x16x32_bf16 v[32:35], v[144:147], v[120:123], v[32:35]
	v_mfma_f32_16x16x32_bf16 v[28:31], v[132:135], v[124:127], v[28:31]
	v_mfma_f32_16x16x32_bf16 v[24:27], v[136:139], v[124:127], v[24:27]
	v_mfma_f32_16x16x32_bf16 v[20:23], v[140:143], v[124:127], v[20:23]
	v_mfma_f32_16x16x32_bf16 v[16:19], v[144:147], v[124:127], v[16:19]
	v_mfma_f32_16x16x32_bf16 v[12:15], v[132:135], v[128:131], v[12:15]
	v_mfma_f32_16x16x32_bf16 v[8:11], v[136:139], v[128:131], v[8:11]
	v_mfma_f32_16x16x32_bf16 v[4:7], v[140:143], v[128:131], v[4:7]
	v_mfma_f32_16x16x32_bf16 v[0:3], v[144:147], v[128:131], v[0:3]
	s_setprio 0
	s_waitcnt vmcnt(0)
	s_add_u32 s36, s36, 0x80
	s_addc_u32 s37, s37, 0
	s_addk_i32 s0, 0x2000
	s_cmpk_lg_i32 s36, 0xf80
	s_waitcnt vmcnt(0)
	s_barrier
	s_cbranch_scc1 .LBB0_1487
	ds_read_b128 v[88:91], v94 offset:16384
	ds_read_b128 v[100:103], v94 offset:18432
	ds_read_b128 v[120:123], v94 offset:20480
	ds_read_b128 v[124:127], v94 offset:22528
	ds_read_b128 v[128:131], v95 offset:49152
	ds_read_b128 v[132:135], v95 offset:51200
	ds_read_b128 v[136:139], v95 offset:53248
	ds_read_b128 v[140:143], v95 offset:55296
	s_setprio 1
	s_waitcnt lgkmcnt(3)
	v_mfma_f32_16x16x32_bf16 v[60:63], v[128:131], v[88:91], v[60:63]
	s_waitcnt lgkmcnt(2)
	v_mfma_f32_16x16x32_bf16 v[56:59], v[132:135], v[88:91], v[56:59]
	s_waitcnt lgkmcnt(1)
	v_mfma_f32_16x16x32_bf16 v[52:55], v[136:139], v[88:91], v[52:55]
	s_waitcnt lgkmcnt(0)
	v_mfma_f32_16x16x32_bf16 v[48:51], v[140:143], v[88:91], v[48:51]
	v_mfma_f32_16x16x32_bf16 v[40:43], v[132:135], v[100:103], v[40:43]
	v_mfma_f32_16x16x32_bf16 v[36:39], v[136:139], v[100:103], v[36:39]
	v_mfma_f32_16x16x32_bf16 v[32:35], v[140:143], v[100:103], v[32:35]
	v_mfma_f32_16x16x32_bf16 v[20:23], v[136:139], v[120:123], v[20:23]
	v_mfma_f32_16x16x32_bf16 v[16:19], v[140:143], v[120:123], v[16:19]
	v_mfma_f32_16x16x32_bf16 v[0:3], v[140:143], v[124:127], v[0:3]
	v_mfma_f32_16x16x32_bf16 v[88:91], v[128:131], v[100:103], v[44:47]
	v_mfma_f32_16x16x32_bf16 v[100:103], v[128:131], v[120:123], v[28:31]
	v_mfma_f32_16x16x32_bf16 v[144:147], v[132:135], v[120:123], v[24:27]
	v_mfma_f32_16x16x32_bf16 v[120:123], v[128:131], v[124:127], v[12:15]
	v_mfma_f32_16x16x32_bf16 v[128:131], v[132:135], v[124:127], v[8:11]
	v_mfma_f32_16x16x32_bf16 v[132:135], v[136:139], v[124:127], v[4:7]
	s_setprio 0
	s_nop 1
	ds_read_b128 v[4:7], v96 offset:16384
	ds_read_b128 v[8:11], v96 offset:18432
	ds_read_b128 v[124:127], v96 offset:20480
	ds_read_b128 v[136:139], v96 offset:22528
	ds_read_b128 v[140:143], v97 offset:49152
	ds_read_b128 v[148:151], v97 offset:51200
	ds_read_b128 v[152:155], v97 offset:53248
	ds_read_b128 v[156:159], v97 offset:55296
	s_setprio 1
	s_waitcnt lgkmcnt(3)
	v_mfma_f32_16x16x32_bf16 v[60:63], v[140:143], v[4:7], v[60:63]
	s_waitcnt lgkmcnt(2)
	v_mfma_f32_16x16x32_bf16 v[44:47], v[148:151], v[4:7], v[56:59]
	s_waitcnt lgkmcnt(1)
	v_mfma_f32_16x16x32_bf16 v[28:31], v[152:155], v[4:7], v[52:55]
	s_waitcnt lgkmcnt(0)
	v_mfma_f32_16x16x32_bf16 v[12:15], v[156:159], v[4:7], v[48:51]
	v_mfma_f32_16x16x32_bf16 v[56:59], v[140:143], v[8:11], v[88:91]
	v_mfma_f32_16x16x32_bf16 v[40:43], v[148:151], v[8:11], v[40:43]
	v_mfma_f32_16x16x32_bf16 v[24:27], v[152:155], v[8:11], v[36:39]
	v_mfma_f32_16x16x32_bf16 v[8:11], v[156:159], v[8:11], v[32:35]
	v_mfma_f32_16x16x32_bf16 v[52:55], v[140:143], v[124:127], v[100:103]
	v_mfma_f32_16x16x32_bf16 v[36:39], v[148:151], v[124:127], v[144:147]
	v_mfma_f32_16x16x32_bf16 v[20:23], v[152:155], v[124:127], v[20:23]
	v_mfma_f32_16x16x32_bf16 v[4:7], v[156:159], v[124:127], v[16:19]
	v_mfma_f32_16x16x32_bf16 v[48:51], v[140:143], v[136:139], v[120:123]
	v_mfma_f32_16x16x32_bf16 v[32:35], v[148:151], v[136:139], v[128:131]
	v_mfma_f32_16x16x32_bf16 v[16:19], v[152:155], v[136:139], v[132:135]
	v_mfma_f32_16x16x32_bf16 v[0:3], v[156:159], v[136:139], v[0:3]
	s_setprio 2
	s_waitcnt vmcnt(0)
	s_cmpk_gt_i32 s1, 0x7f
	s_barrier
	s_cbranch_scc0 .LBB0_1490
	s_add_i32 s0, s24, 0xffffc000
	s_lshr_b32 s0, s0, 8
	v_readlane_b32 s6, v180, 24
	s_add_i32 s6, s0, s6
	s_and_b32 s10, s24, 0x80
	s_lshl_b64 s[8:9], s[6:7], 8
	v_readlane_b32 s36, v182, 19
	s_or_b32 s8, s8, s10
	s_mov_b64 s[10:11], 0
	v_readlane_b32 s37, v182, 20
	s_branch .LBB0_1491

.LBB0_1498:
	s_setprio 3
	s_and_b32 s10, s6, 0x2000
	s_xor_b32 s8, s10, 0x2000
	s_lshl_b32 s101, s8, 1
	s_add_u32 s101, s101, s100
	s_add_u32 m0, s101, 0x0
	s_nop 0
	global_load_lds_dwordx4 v[184:185], off
	s_add_u32 m0, s101, 0x1000
	v_lshl_add_u64 v[184:185], v[184:185], 0, vcc
	global_load_lds_dwordx4 v[186:187], off
	s_add_u32 m0, s101, 0x2000
	v_lshl_add_u64 v[186:187], v[186:187], 0, vcc
	global_load_lds_dwordx4 v[188:189], off
	s_add_u32 m0, s101, 0x3000
	v_lshl_add_u64 v[188:189], v[188:189], 0, vcc
	global_load_lds_dwordx4 v[190:191], off
	s_add_u32 m0, s101, 0x8000
	v_lshl_add_u64 v[190:191], v[190:191], 0, vcc
	global_load_lds_dwordx4 v[192:193], off
	s_add_u32 m0, s101, 0x9000
	v_lshl_add_u64 v[192:193], v[192:193], 0, vcc
	global_load_lds_dwordx4 v[194:195], off
	s_add_u32 m0, s101, 0xa000
	v_lshl_add_u64 v[194:195], v[194:195], 0, vcc
	global_load_lds_dwordx4 v[196:197], off
	s_add_u32 m0, s101, 0xb000
	v_lshl_add_u64 v[196:197], v[196:197], 0, vcc
	global_load_lds_dwordx4 v[198:199], off
	v_lshl_add_u64 v[198:199], v[198:199], 0, vcc
	s_lshl_b32 s8, s10, 1
	v_add_u32_e32 v68, s8, v84
	v_add_u32_e32 v140, s8, v83
	v_add_u32_e32 v120, v68, v90
	v_add_u32_e32 v136, v140, v90
	ds_read_b128 v[92:95], v120
	ds_read_b128 v[96:99], v120 offset:2048
	ds_read_b128 v[100:103], v120 offset:4096
	ds_read_b128 v[120:123], v120 offset:6144
	ds_read_b128 v[124:127], v136 offset:32768
	ds_read_b128 v[128:131], v136 offset:34816
	ds_read_b128 v[132:135], v136 offset:36864
	ds_read_b128 v[136:139], v136 offset:38912
	s_setprio 1
	s_waitcnt lgkmcnt(0)
	v_mfma_f32_16x16x32_bf16 v[60:63], v[124:127], v[92:95], v[60:63]
	v_mfma_f32_16x16x32_bf16 v[56:59], v[128:131], v[92:95], v[56:59]
	v_mfma_f32_16x16x32_bf16 v[52:55], v[132:135], v[92:95], v[52:55]
	v_mfma_f32_16x16x32_bf16 v[48:51], v[136:139], v[92:95], v[48:51]
	v_mfma_f32_16x16x32_bf16 v[44:47], v[124:127], v[96:99], v[44:47]
	v_mfma_f32_16x16x32_bf16 v[40:43], v[128:131], v[96:99], v[40:43]
	v_mfma_f32_16x16x32_bf16 v[36:39], v[132:135], v[96:99], v[36:39]
	v_mfma_f32_16x16x32_bf16 v[32:35], v[136:139], v[96:99], v[32:35]
	v_mfma_f32_16x16x32_bf16 v[28:31], v[124:127], v[100:103], v[28:31]
	v_mfma_f32_16x16x32_bf16 v[24:27], v[128:131], v[100:103], v[24:27]
	v_mfma_f32_16x16x32_bf16 v[20:23], v[132:135], v[100:103], v[20:23]
	v_mfma_f32_16x16x32_bf16 v[16:19], v[136:139], v[100:103], v[16:19]
	v_mfma_f32_16x16x32_bf16 v[12:15], v[124:127], v[120:123], v[12:15]
	v_mfma_f32_16x16x32_bf16 v[8:11], v[128:131], v[120:123], v[8:11]
	v_mfma_f32_16x16x32_bf16 v[4:7], v[132:135], v[120:123], v[4:7]
	v_mfma_f32_16x16x32_bf16 v[0:3], v[136:139], v[120:123], v[0:3]
	s_setprio 0
	v_add_u32_e32 v68, v68, v91
	ds_read_b128 v[92:95], v68
	ds_read_b128 v[96:99], v68 offset:2048
	ds_read_b128 v[100:103], v68 offset:4096
	ds_read_b128 v[120:123], v68 offset:6144
	v_add_u32_e32 v68, v140, v91
	ds_read_b128 v[124:127], v68 offset:32768
	ds_read_b128 v[128:131], v68 offset:34816
	ds_read_b128 v[132:135], v68 offset:36864
	ds_read_b128 v[136:139], v68 offset:38912
	s_setprio 1
	s_waitcnt lgkmcnt(0)
	v_mfma_f32_16x16x32_bf16 v[60:63], v[124:127], v[92:95], v[60:63]
	v_mfma_f32_16x16x32_bf16 v[56:59], v[128:131], v[92:95], v[56:59]
	v_mfma_f32_16x16x32_bf16 v[52:55], v[132:135], v[92:95], v[52:55]
	v_mfma_f32_16x16x32_bf16 v[48:51], v[136:139], v[92:95], v[48:51]
	v_mfma_f32_16x16x32_bf16 v[44:47], v[124:127], v[96:99], v[44:47]
	v_mfma_f32_16x16x32_bf16 v[40:43], v[128:131], v[96:99], v[40:43]
	v_mfma_f32_16x16x32_bf16 v[36:39], v[132:135], v[96:99], v[36:39]
	v_mfma_f32_16x16x32_bf16 v[32:35], v[136:139], v[96:99], v[32:35]
	v_mfma_f32_16x16x32_bf16 v[28:31], v[124:127], v[100:103], v[28:31]
	v_mfma_f32_16x16x32_bf16 v[24:27], v[128:131], v[100:103], v[24:27]
	v_mfma_f32_16x16x32_bf16 v[20:23], v[132:135], v[100:103], v[20:23]
	v_mfma_f32_16x16x32_bf16 v[16:19], v[136:139], v[100:103], v[16:19]
	v_mfma_f32_16x16x32_bf16 v[12:15], v[124:127], v[120:123], v[12:15]
	v_mfma_f32_16x16x32_bf16 v[8:11], v[128:131], v[120:123], v[8:11]
	v_mfma_f32_16x16x32_bf16 v[4:7], v[132:135], v[120:123], v[4:7]
	v_mfma_f32_16x16x32_bf16 v[0:3], v[136:139], v[120:123], v[0:3]
	s_setprio 0
	s_addk_i32 s6, 0x2000
	s_waitcnt vmcnt(0)
	s_add_u32 s36, s36, 0x80
	s_addc_u32 s37, s37, 0
	s_cmpk_lg_i32 s36, 0x780
	s_waitcnt vmcnt(0)
	s_barrier
	s_cbranch_scc1 .LBB0_1498
	ds_read_b128 v[78:81], v85 offset:55296
	ds_read_b128 v[92:95], v85 offset:53248
	ds_read_b128 v[96:99], v85 offset:51200
	ds_read_b128 v[100:103], v85 offset:49152
	ds_read_b128 v[120:123], v86 offset:22528
	ds_read_b128 v[124:127], v86 offset:20480
	ds_read_b128 v[128:131], v86 offset:18432
	ds_read_b128 v[132:135], v86 offset:16384
	s_setprio 1
	s_waitcnt lgkmcnt(0)
	v_mfma_f32_16x16x32_bf16 v[60:63], v[100:103], v[132:135], v[60:63]
	v_mfma_f32_16x16x32_bf16 v[56:59], v[96:99], v[132:135], v[56:59]
	v_mfma_f32_16x16x32_bf16 v[52:55], v[92:95], v[132:135], v[52:55]
	v_mfma_f32_16x16x32_bf16 v[48:51], v[78:81], v[132:135], v[48:51]
	v_mfma_f32_16x16x32_bf16 v[44:47], v[100:103], v[128:131], v[44:47]
	v_mfma_f32_16x16x32_bf16 v[40:43], v[96:99], v[128:131], v[40:43]
	v_mfma_f32_16x16x32_bf16 v[36:39], v[92:95], v[128:131], v[36:39]
	v_mfma_f32_16x16x32_bf16 v[32:35], v[78:81], v[128:131], v[32:35]
	v_mfma_f32_16x16x32_bf16 v[28:31], v[100:103], v[124:127], v[28:31]
	v_mfma_f32_16x16x32_bf16 v[24:27], v[96:99], v[124:127], v[24:27]
	v_mfma_f32_16x16x32_bf16 v[20:23], v[92:95], v[124:127], v[20:23]
	v_mfma_f32_16x16x32_bf16 v[16:19], v[78:81], v[124:127], v[16:19]
	v_mfma_f32_16x16x32_bf16 v[12:15], v[100:103], v[120:123], v[12:15]
	v_mfma_f32_16x16x32_bf16 v[8:11], v[96:99], v[120:123], v[8:11]
	v_mfma_f32_16x16x32_bf16 v[4:7], v[92:95], v[120:123], v[4:7]
	v_mfma_f32_16x16x32_bf16 v[0:3], v[78:81], v[120:123], v[0:3]
	s_setprio 0
	ds_read_b128 v[78:81], v87 offset:16384
	ds_read_b128 v[92:95], v87 offset:18432
	ds_read_b128 v[96:99], v87 offset:20480
	ds_read_b128 v[100:103], v87 offset:22528
	ds_read_b128 v[120:123], v88 offset:49152
	ds_read_b128 v[124:127], v88 offset:51200
	ds_read_b128 v[128:131], v88 offset:53248
	ds_read_b128 v[132:135], v88 offset:55296
	s_setprio 1
	s_waitcnt lgkmcnt(3)
	v_mfma_f32_16x16x32_bf16 v[60:63], v[120:123], v[78:81], v[60:63]
	s_waitcnt lgkmcnt(2)
	v_mfma_f32_16x16x32_bf16 v[56:59], v[124:127], v[78:81], v[56:59]
	s_waitcnt lgkmcnt(1)
	v_mfma_f32_16x16x32_bf16 v[52:55], v[128:131], v[78:81], v[52:55]
	s_waitcnt lgkmcnt(0)
	v_mfma_f32_16x16x32_bf16 v[48:51], v[132:135], v[78:81], v[48:51]
	v_mfma_f32_16x16x32_bf16 v[44:47], v[120:123], v[92:95], v[44:47]
	v_mfma_f32_16x16x32_bf16 v[40:43], v[124:127], v[92:95], v[40:43]
	v_mfma_f32_16x16x32_bf16 v[36:39], v[128:131], v[92:95], v[36:39]
	v_mfma_f32_16x16x32_bf16 v[32:35], v[132:135], v[92:95], v[32:35]
	v_mfma_f32_16x16x32_bf16 v[28:31], v[120:123], v[96:99], v[28:31]
	v_mfma_f32_16x16x32_bf16 v[24:27], v[124:127], v[96:99], v[24:27]
	v_mfma_f32_16x16x32_bf16 v[20:23], v[128:131], v[96:99], v[20:23]
	v_mfma_f32_16x16x32_bf16 v[16:19], v[132:135], v[96:99], v[16:19]
	v_mfma_f32_16x16x32_bf16 v[12:15], v[120:123], v[100:103], v[12:15]
	v_mfma_f32_16x16x32_bf16 v[8:11], v[124:127], v[100:103], v[8:11]
	v_mfma_f32_16x16x32_bf16 v[4:7], v[128:131], v[100:103], v[4:7]
	v_mfma_f32_16x16x32_bf16 v[0:3], v[132:135], v[100:103], v[0:3]
	s_setprio 2
	s_ashr_i32 s1, s1, 4
	s_mul_hi_i32 s6, s1, 0x4200000
	s_mul_i32 s1, s1, 0x4200000
	s_add_u32 s8, s90, s1
	v_add_u32_e32 v78, s20, v71
	s_addc_u32 s9, s91, s6
	s_and_b32 s1, s24, 0x780
	v_ashrrev_i32_e32 v79, 31, v78
	v_or_b32_e32 v68, s1, v89
	v_lshlrev_b64 v[80:81], 12, v[78:79]
	v_lshl_add_u64 v[80:81], s[8:9], 0, v[80:81]
	v_lshlrev_b32_e32 v68, 1, v68
	v_cvt_pk_bf16_f32 v60, v60, v61
	v_cvt_pk_bf16_f32 v61, v62, v63
	v_lshl_add_u64 v[62:63], v[80:81], 0, v[68:69]
	v_cvt_pk_bf16_f32 v48, v48, v49
	v_cvt_pk_bf16_f32 v49, v50, v51
	s_waitcnt vmcnt(0)
	s_barrier
	global_store_dwordx2 v[62:63], v[48:49], off offset:96
	v_or_b32_e32 v48, 16, v78
	v_ashrrev_i32_e32 v49, 31, v48
	v_lshlrev_b64 v[48:49], 12, v[48:49]
	v_lshl_add_u64 v[48:49], s[8:9], 0, v[48:49]
	v_cvt_pk_bf16_f32 v44, v44, v45
	v_cvt_pk_bf16_f32 v45, v46, v47
	v_lshl_add_u64 v[46:47], v[48:49], 0, v[68:69]
	v_cvt_pk_bf16_f32 v32, v32, v33
	v_cvt_pk_bf16_f32 v33, v34, v35
	global_store_dwordx2 v[46:47], v[32:33], off offset:96
	v_or_b32_e32 v32, 32, v78
	v_ashrrev_i32_e32 v33, 31, v32
	v_lshlrev_b64 v[32:33], 12, v[32:33]
	v_lshl_add_u64 v[32:33], s[8:9], 0, v[32:33]
	v_cvt_pk_bf16_f32 v28, v28, v29
	v_cvt_pk_bf16_f32 v29, v30, v31
	v_lshl_add_u64 v[30:31], v[32:33], 0, v[68:69]
	v_cvt_pk_bf16_f32 v16, v16, v17
	v_cvt_pk_bf16_f32 v17, v18, v19
	global_store_dwordx2 v[30:31], v[16:17], off offset:96
	v_or_b32_e32 v16, 48, v78
	v_ashrrev_i32_e32 v17, 31, v16
	v_lshlrev_b64 v[16:17], 12, v[16:17]
	v_lshl_add_u64 v[16:17], s[8:9], 0, v[16:17]
	s_add_i32 s0, s0, s84
	v_cvt_pk_bf16_f32 v56, v56, v57
	v_cvt_pk_bf16_f32 v57, v58, v59
	v_cvt_pk_bf16_f32 v52, v52, v53
	v_cvt_pk_bf16_f32 v53, v54, v55
	v_cvt_pk_bf16_f32 v40, v40, v41
	v_cvt_pk_bf16_f32 v41, v42, v43
	v_cvt_pk_bf16_f32 v36, v36, v37
	v_cvt_pk_bf16_f32 v37, v38, v39
	v_cvt_pk_bf16_f32 v24, v24, v25
	v_cvt_pk_bf16_f32 v25, v26, v27
	v_cvt_pk_bf16_f32 v20, v20, v21
	v_cvt_pk_bf16_f32 v21, v22, v23
	v_cvt_pk_bf16_f32 v12, v12, v13
	v_cvt_pk_bf16_f32 v13, v14, v15
	v_lshl_add_u64 v[14:15], v[16:17], 0, v[68:69]
	v_cvt_pk_bf16_f32 v8, v8, v9
	v_cvt_pk_bf16_f32 v9, v10, v11
	v_cvt_pk_bf16_f32 v4, v4, v5
	v_cvt_pk_bf16_f32 v5, v6, v7
	v_cvt_pk_bf16_f32 v0, v0, v1
	v_cvt_pk_bf16_f32 v1, v2, v3
	s_cmpk_lt_i32 s0, 0x18c0
	global_store_dwordx2 v[62:63], v[60:61], off
	global_store_dwordx2 v[62:63], v[56:57], off offset:32
	global_store_dwordx2 v[62:63], v[52:53], off offset:64
	global_store_dwordx2 v[46:47], v[44:45], off
	global_store_dwordx2 v[46:47], v[40:41], off offset:32
	global_store_dwordx2 v[46:47], v[36:37], off offset:64
	global_store_dwordx2 v[30:31], v[28:29], off
	global_store_dwordx2 v[30:31], v[24:25], off offset:32
	global_store_dwordx2 v[30:31], v[20:21], off offset:64
	global_store_dwordx2 v[14:15], v[12:13], off
	global_store_dwordx2 v[14:15], v[8:9], off offset:32
	global_store_dwordx2 v[14:15], v[4:5], off offset:64
	global_store_dwordx2 v[14:15], v[0:1], off offset:96
	s_cbranch_scc1 .LBB0_1497

.LBB0_1707:
	s_setprio 3
	s_and_b32 s6, s0, 0x2000
	s_xor_b32 s8, s6, 0x2000
	s_lshl_b32 s101, s8, 1
	s_add_u32 s101, s101, s100
	s_add_u32 m0, s101, 0x0
	s_nop 0
	global_load_lds_dwordx4 v[184:185], off
	s_add_u32 m0, s101, 0x1000
	v_lshl_add_u64 v[184:185], v[184:185], 0, vcc
	global_load_lds_dwordx4 v[186:187], off
	s_add_u32 m0, s101, 0x2000
	v_lshl_add_u64 v[186:187], v[186:187], 0, vcc
	global_load_lds_dwordx4 v[188:189], off
	s_add_u32 m0, s101, 0x3000
	v_lshl_add_u64 v[188:189], v[188:189], 0, vcc
	global_load_lds_dwordx4 v[190:191], off
	s_add_u32 m0, s101, 0x8000
	v_lshl_add_u64 v[190:191], v[190:191], 0, vcc
	global_load_lds_dwordx4 v[192:193], off
	s_add_u32 m0, s101, 0x9000
	v_lshl_add_u64 v[192:193], v[192:193], 0, vcc
	global_load_lds_dwordx4 v[194:195], off
	s_add_u32 m0, s101, 0xa000
	v_lshl_add_u64 v[194:195], v[194:195], 0, vcc
	global_load_lds_dwordx4 v[196:197], off
	s_add_u32 m0, s101, 0xb000
	v_lshl_add_u64 v[196:197], v[196:197], 0, vcc
	global_load_lds_dwordx4 v[198:199], off
	v_lshl_add_u64 v[198:199], v[198:199], 0, vcc
	s_lshl_b32 s6, s6, 1
	v_add_u32_e32 v102, s6, v90
	v_add_u32_e32 v103, s6, v71
	v_add_u32_e32 v128, v102, v96
	v_add_u32_e32 v144, v103, v96
	ds_read_b128 v[98:101], v128
	ds_read_b128 v[120:123], v128 offset:2048
	ds_read_b128 v[124:127], v128 offset:4096
	ds_read_b128 v[128:131], v128 offset:6144
	ds_read_b128 v[132:135], v144 offset:32768
	ds_read_b128 v[136:139], v144 offset:34816
	ds_read_b128 v[140:143], v144 offset:36864
	ds_read_b128 v[144:147], v144 offset:38912
	s_setprio 1
	s_waitcnt lgkmcnt(0)
	v_mfma_f32_16x16x32_bf16 v[60:63], v[132:135], v[98:101], v[60:63]
	v_mfma_f32_16x16x32_bf16 v[56:59], v[136:139], v[98:101], v[56:59]
	v_mfma_f32_16x16x32_bf16 v[52:55], v[140:143], v[98:101], v[52:55]
	v_mfma_f32_16x16x32_bf16 v[48:51], v[144:147], v[98:101], v[48:51]
	v_mfma_f32_16x16x32_bf16 v[44:47], v[132:135], v[120:123], v[44:47]
	v_mfma_f32_16x16x32_bf16 v[40:43], v[136:139], v[120:123], v[40:43]
	v_mfma_f32_16x16x32_bf16 v[36:39], v[140:143], v[120:123], v[36:39]
	v_mfma_f32_16x16x32_bf16 v[32:35], v[144:147], v[120:123], v[32:35]
	v_mfma_f32_16x16x32_bf16 v[28:31], v[132:135], v[124:127], v[28:31]
	v_mfma_f32_16x16x32_bf16 v[24:27], v[136:139], v[124:127], v[24:27]
	v_mfma_f32_16x16x32_bf16 v[20:23], v[140:143], v[124:127], v[20:23]
	v_mfma_f32_16x16x32_bf16 v[16:19], v[144:147], v[124:127], v[16:19]
	v_mfma_f32_16x16x32_bf16 v[12:15], v[132:135], v[128:131], v[12:15]
	v_mfma_f32_16x16x32_bf16 v[8:11], v[136:139], v[128:131], v[8:11]
	v_mfma_f32_16x16x32_bf16 v[4:7], v[140:143], v[128:131], v[4:7]
	v_mfma_f32_16x16x32_bf16 v[0:3], v[144:147], v[128:131], v[0:3]
	s_setprio 0
	v_add_u32_e32 v102, v102, v97
	ds_read_b128 v[98:101], v102
	ds_read_b128 v[120:123], v102 offset:2048
	ds_read_b128 v[124:127], v102 offset:4096
	ds_read_b128 v[128:131], v102 offset:6144
	v_add_u32_e32 v102, v103, v97
	ds_read_b128 v[132:135], v102 offset:32768
	ds_read_b128 v[136:139], v102 offset:34816
	ds_read_b128 v[140:143], v102 offset:36864
	ds_read_b128 v[144:147], v102 offset:38912
	s_setprio 1
	s_waitcnt lgkmcnt(0)
	v_mfma_f32_16x16x32_bf16 v[60:63], v[132:135], v[98:101], v[60:63]
	v_mfma_f32_16x16x32_bf16 v[56:59], v[136:139], v[98:101], v[56:59]
	v_mfma_f32_16x16x32_bf16 v[52:55], v[140:143], v[98:101], v[52:55]
	v_mfma_f32_16x16x32_bf16 v[48:51], v[144:147], v[98:101], v[48:51]
	v_mfma_f32_16x16x32_bf16 v[44:47], v[132:135], v[120:123], v[44:47]
	v_mfma_f32_16x16x32_bf16 v[40:43], v[136:139], v[120:123], v[40:43]
	v_mfma_f32_16x16x32_bf16 v[36:39], v[140:143], v[120:123], v[36:39]
	v_mfma_f32_16x16x32_bf16 v[32:35], v[144:147], v[120:123], v[32:35]
	v_mfma_f32_16x16x32_bf16 v[28:31], v[132:135], v[124:127], v[28:31]
	v_mfma_f32_16x16x32_bf16 v[24:27], v[136:139], v[124:127], v[24:27]
	v_mfma_f32_16x16x32_bf16 v[20:23], v[140:143], v[124:127], v[20:23]
	v_mfma_f32_16x16x32_bf16 v[16:19], v[144:147], v[124:127], v[16:19]
	v_mfma_f32_16x16x32_bf16 v[12:15], v[132:135], v[128:131], v[12:15]
	v_mfma_f32_16x16x32_bf16 v[8:11], v[136:139], v[128:131], v[8:11]
	v_mfma_f32_16x16x32_bf16 v[4:7], v[140:143], v[128:131], v[4:7]
	v_mfma_f32_16x16x32_bf16 v[0:3], v[144:147], v[128:131], v[0:3]
	s_setprio 0
	s_waitcnt vmcnt(0)
	s_add_u32 s36, s36, 0x80
	s_addc_u32 s37, s37, 0
	s_addk_i32 s0, 0x2000
	s_cmpk_lg_i32 s36, 0xf80
	s_waitcnt vmcnt(0)
	s_barrier
	s_cbranch_scc1 .LBB0_1707
	ds_read_b128 v[86:89], v92 offset:16384
	ds_read_b128 v[98:101], v92 offset:18432
	ds_read_b128 v[120:123], v92 offset:20480
	ds_read_b128 v[124:127], v92 offset:22528
	ds_read_b128 v[128:131], v93 offset:49152
	ds_read_b128 v[132:135], v93 offset:51200
	ds_read_b128 v[136:139], v93 offset:53248
	ds_read_b128 v[140:143], v93 offset:55296
	s_setprio 1
	s_waitcnt lgkmcnt(3)
	v_mfma_f32_16x16x32_bf16 v[60:63], v[128:131], v[86:89], v[60:63]
	s_waitcnt lgkmcnt(2)
	v_mfma_f32_16x16x32_bf16 v[56:59], v[132:135], v[86:89], v[56:59]
	s_waitcnt lgkmcnt(1)
	v_mfma_f32_16x16x32_bf16 v[52:55], v[136:139], v[86:89], v[52:55]
	s_waitcnt lgkmcnt(0)
	v_mfma_f32_16x16x32_bf16 v[48:51], v[140:143], v[86:89], v[48:51]
	v_mfma_f32_16x16x32_bf16 v[40:43], v[132:135], v[98:101], v[40:43]
	v_mfma_f32_16x16x32_bf16 v[36:39], v[136:139], v[98:101], v[36:39]
	v_mfma_f32_16x16x32_bf16 v[32:35], v[140:143], v[98:101], v[32:35]
	v_mfma_f32_16x16x32_bf16 v[20:23], v[136:139], v[120:123], v[20:23]
	v_mfma_f32_16x16x32_bf16 v[16:19], v[140:143], v[120:123], v[16:19]
	v_mfma_f32_16x16x32_bf16 v[0:3], v[140:143], v[124:127], v[0:3]
	v_mfma_f32_16x16x32_bf16 v[86:89], v[128:131], v[98:101], v[44:47]
	v_mfma_f32_16x16x32_bf16 v[98:101], v[128:131], v[120:123], v[28:31]
	v_mfma_f32_16x16x32_bf16 v[144:147], v[132:135], v[120:123], v[24:27]
	v_mfma_f32_16x16x32_bf16 v[120:123], v[128:131], v[124:127], v[12:15]
	v_mfma_f32_16x16x32_bf16 v[128:131], v[132:135], v[124:127], v[8:11]
	v_mfma_f32_16x16x32_bf16 v[132:135], v[136:139], v[124:127], v[4:7]
	s_setprio 0
	s_nop 1
	ds_read_b128 v[4:7], v94 offset:16384
	ds_read_b128 v[8:11], v94 offset:18432
	ds_read_b128 v[124:127], v94 offset:20480
	ds_read_b128 v[136:139], v94 offset:22528
	ds_read_b128 v[140:143], v95 offset:49152
	ds_read_b128 v[148:151], v95 offset:51200
	ds_read_b128 v[152:155], v95 offset:53248
	ds_read_b128 v[156:159], v95 offset:55296
	s_setprio 1
	s_waitcnt lgkmcnt(3)
	v_mfma_f32_16x16x32_bf16 v[60:63], v[140:143], v[4:7], v[60:63]
	s_waitcnt lgkmcnt(2)
	v_mfma_f32_16x16x32_bf16 v[44:47], v[148:151], v[4:7], v[56:59]
	s_waitcnt lgkmcnt(1)
	v_mfma_f32_16x16x32_bf16 v[28:31], v[152:155], v[4:7], v[52:55]
	s_waitcnt lgkmcnt(0)
	v_mfma_f32_16x16x32_bf16 v[12:15], v[156:159], v[4:7], v[48:51]
	v_mfma_f32_16x16x32_bf16 v[56:59], v[140:143], v[8:11], v[86:89]
	v_mfma_f32_16x16x32_bf16 v[40:43], v[148:151], v[8:11], v[40:43]
	v_mfma_f32_16x16x32_bf16 v[24:27], v[152:155], v[8:11], v[36:39]
	v_mfma_f32_16x16x32_bf16 v[8:11], v[156:159], v[8:11], v[32:35]
	v_mfma_f32_16x16x32_bf16 v[52:55], v[140:143], v[124:127], v[98:101]
	v_mfma_f32_16x16x32_bf16 v[36:39], v[148:151], v[124:127], v[144:147]
	v_mfma_f32_16x16x32_bf16 v[20:23], v[152:155], v[124:127], v[20:23]
	v_mfma_f32_16x16x32_bf16 v[4:7], v[156:159], v[124:127], v[16:19]
	v_mfma_f32_16x16x32_bf16 v[48:51], v[140:143], v[136:139], v[120:123]
	v_mfma_f32_16x16x32_bf16 v[32:35], v[148:151], v[136:139], v[128:131]
	v_mfma_f32_16x16x32_bf16 v[16:19], v[152:155], v[136:139], v[132:135]
	v_mfma_f32_16x16x32_bf16 v[0:3], v[156:159], v[136:139], v[0:3]
	s_setprio 2
	s_waitcnt vmcnt(0)
	s_cmpk_gt_i32 s1, 0x7f
	s_barrier
	s_cbranch_scc0 .LBB0_1710
	s_add_i32 s0, s24, 0xffffc000
	s_lshr_b32 s0, s0, 8
	v_readlane_b32 s6, v180, 24
	s_add_i32 s6, s0, s6
	s_and_b32 s10, s24, 0x80
	s_lshl_b64 s[8:9], s[6:7], 8
	v_readlane_b32 s36, v182, 19
	s_or_b32 s8, s8, s10
	s_mov_b64 s[10:11], 0
	v_readlane_b32 s37, v182, 20
	s_branch .LBB0_1711
